# phase 4: retention scans interleaved into the attention item sequence at a class-dependent slot (8 classes of 4 sibling workgroups, slots 0,1,2,3,5,0,2,5)
# baseline (speedup 1.0000x reference)
.Lp4_attn_entry:
	s_mov_b32 s0, s35
	s_mov_b32 s1, s98
	s_mov_b32 s4, -1
	v_mbcnt_lo_u32_b32 v0, -1, 0
	v_readlane_b32 s6, v252, 0
	v_mbcnt_hi_u32_b32 v0, s4, v0
	v_lshl_add_u32 v2, s1, 6, v0
	s_cmpk_gt_i32 s6, 0x4ff
	v_readfirstlane_b32 s4, v2
	s_cbranch_scc1 .LBB0_43
	v_readlane_b32 s5, v255, 62
	s_nop 3
	s_cmp_eq_u32 s5, 2
	s_cbranch_scc0 .Lp4_first
	v_readlane_b32 s6, v255, 61
	s_nop 3
	s_cmpk_gt_i32 s6, 0x4ff
	s_cbranch_scc0 .Lp4_go_attn
	s_mov_b32 s5, 0
	s_nop 0
	v_writelane_b32 v255, s5, 62
	s_branch .LBB0_94
.Lp4_first:
	s_bfe_u32 s5, s6, 0x30005
	s_lshl_b32 s5, s5, 2
	s_lshr_b32 s5, 0x52053210, s5
	s_and_b32 s5, s5, 15
	s_nop 0
	v_writelane_b32 v255, s5, 60
	s_nop 1
	v_writelane_b32 v255, s6, 61
	s_cmp_eq_u32 s5, 0
	s_cbranch_scc1 .LBB0_43

.LBB0_41:
	v_lshl_add_u64 v[10:11], v[8:9], 0, s[0:1]
	v_add_co_u32_e32 v12, vcc, 0x219b000, v10
	v_add_u32_e32 v14, s4, v189
	s_nop 0
	v_addc_co_u32_e32 v13, vcc, 0, v11, vcc
	global_load_dwordx4 v[16:19], v[12:13], off offset:1536
	ds_read_b128 v[2:5], v14
	s_mov_b32 s5, 0x3739b000
	s_add_i32 s4, s4, 0x8800
	v_lshl_add_u64 v[8:9], v[8:9], 0, s[16:17]
	s_cmp_eq_u32 s4, 0x11000
	s_waitcnt lgkmcnt(0)
	v_lshlrev_b32_e32 v12, 16, v2
	v_and_b32_e32 v13, 0xffff0000, v2
	s_waitcnt vmcnt(0)
	v_lshlrev_b32_e32 v15, 16, v16
	v_and_b32_e32 v2, 0xffff0000, v16
	v_mul_f32_e32 v16, 0xbfb8aa3b, v15
	v_exp_f32_e32 v20, v16
	v_mul_f32_e32 v16, 0xbfb8aa3b, v2
	v_exp_f32_e32 v21, v16
	s_nop 0
	v_pk_add_f32 v[20:21], v[20:21], 1.0 op_sel_hi:[1,0]
	s_nop 0
	v_div_scale_f32 v16, s[10:11], v21, v21, v2
	v_rcp_f32_e32 v22, v16
	s_nop 0
	v_fma_f32 v23, -v16, v22, 1.0
	v_fmac_f32_e32 v22, v23, v22
	v_div_scale_f32 v23, vcc, v2, v21, v2
	v_mul_f32_e32 v24, v23, v22
	v_fma_f32 v25, -v16, v24, v23
	v_fmac_f32_e32 v24, v25, v22
	v_fma_f32 v16, -v16, v24, v23
	v_div_fmas_f32 v16, v16, v22, v24
	v_div_fixup_f32 v21, v16, v21, v2
	v_div_scale_f32 v2, s[10:11], v20, v20, v15
	v_rcp_f32_e32 v16, v2
	s_nop 0
	v_fma_f32 v22, -v2, v16, 1.0
	v_fmac_f32_e32 v16, v22, v16
	v_div_scale_f32 v22, vcc, v15, v20, v15
	v_mul_f32_e32 v23, v22, v16
	v_fma_f32 v24, -v2, v23, v22
	v_fmac_f32_e32 v23, v24, v16
	v_fma_f32 v2, -v2, v23, v22
	v_div_fmas_f32 v2, v2, v16, v23
	v_div_fixup_f32 v20, v2, v20, v15
	v_pk_mul_f32 v[12:13], v[20:21], v[12:13]
	v_lshlrev_b32_e32 v15, 16, v17
	v_cvt_pk_bf16_f32 v2, v12, v13
	v_lshlrev_b32_e32 v12, 16, v3
	v_and_b32_e32 v13, 0xffff0000, v3
	v_and_b32_e32 v3, 0xffff0000, v17
	v_mul_f32_e32 v16, 0xbfb8aa3b, v15
	v_mul_f32_e32 v17, 0xbfb8aa3b, v3
	v_exp_f32_e32 v16, v16
	v_exp_f32_e32 v17, v17
	s_nop 0
	v_pk_add_f32 v[16:17], v[16:17], 1.0 op_sel_hi:[1,0]
	s_nop 0
	v_div_scale_f32 v20, s[10:11], v17, v17, v3
	v_rcp_f32_e32 v21, v20
	s_nop 0
	v_fma_f32 v22, -v20, v21, 1.0
	v_fmac_f32_e32 v21, v22, v21
	v_div_scale_f32 v22, vcc, v3, v17, v3
	v_mul_f32_e32 v23, v22, v21
	v_fma_f32 v24, -v20, v23, v22
	v_fmac_f32_e32 v23, v24, v21
	v_fma_f32 v20, -v20, v23, v22
	v_div_fmas_f32 v20, v20, v21, v23
	v_div_fixup_f32 v17, v20, v17, v3
	v_div_scale_f32 v3, s[10:11], v16, v16, v15
	v_rcp_f32_e32 v20, v3
	s_nop 0
	v_fma_f32 v21, -v3, v20, 1.0
	v_fmac_f32_e32 v20, v21, v20
	v_div_scale_f32 v21, vcc, v15, v16, v15
	v_mul_f32_e32 v22, v21, v20
	v_fma_f32 v23, -v3, v22, v21
	v_fmac_f32_e32 v22, v23, v20
	v_fma_f32 v3, -v3, v22, v21
	v_div_fmas_f32 v3, v3, v20, v22
	v_div_fixup_f32 v16, v3, v16, v15
	v_pk_mul_f32 v[12:13], v[16:17], v[12:13]
	v_lshlrev_b32_e32 v15, 16, v18
	v_cvt_pk_bf16_f32 v3, v12, v13
	v_lshlrev_b32_e32 v12, 16, v4
	v_and_b32_e32 v13, 0xffff0000, v4
	v_and_b32_e32 v4, 0xffff0000, v18
	v_mul_f32_e32 v16, 0xbfb8aa3b, v15
	v_mul_f32_e32 v17, 0xbfb8aa3b, v4
	v_exp_f32_e32 v16, v16
	v_exp_f32_e32 v17, v17
	s_nop 0
	v_pk_add_f32 v[16:17], v[16:17], 1.0 op_sel_hi:[1,0]
	s_nop 0
	v_div_scale_f32 v18, s[10:11], v17, v17, v4
	v_rcp_f32_e32 v20, v18
	s_nop 0
	v_fma_f32 v21, -v18, v20, 1.0
	v_fmac_f32_e32 v20, v21, v20
	v_div_scale_f32 v21, vcc, v4, v17, v4
	v_mul_f32_e32 v22, v21, v20
	v_fma_f32 v23, -v18, v22, v21
	v_fmac_f32_e32 v22, v23, v20
	v_fma_f32 v18, -v18, v22, v21
	v_div_fmas_f32 v18, v18, v20, v22
	v_div_fixup_f32 v17, v18, v17, v4
	v_div_scale_f32 v4, s[10:11], v16, v16, v15
	v_rcp_f32_e32 v18, v4
	s_nop 0
	v_fma_f32 v20, -v4, v18, 1.0
	v_fmac_f32_e32 v18, v20, v18
	v_div_scale_f32 v20, vcc, v15, v16, v15
	v_mul_f32_e32 v21, v20, v18
	v_fma_f32 v22, -v4, v21, v20
	v_fmac_f32_e32 v21, v22, v18
	v_fma_f32 v4, -v4, v21, v20
	v_div_fmas_f32 v4, v4, v18, v21
	v_div_fixup_f32 v16, v4, v16, v15
	v_pk_mul_f32 v[12:13], v[16:17], v[12:13]
	v_lshlrev_b32_e32 v15, 16, v19
	v_cvt_pk_bf16_f32 v4, v12, v13
	v_lshlrev_b32_e32 v12, 16, v5
	v_and_b32_e32 v13, 0xffff0000, v5
	v_and_b32_e32 v5, 0xffff0000, v19
	v_mul_f32_e32 v16, 0xbfb8aa3b, v15
	v_mul_f32_e32 v17, 0xbfb8aa3b, v5
	v_exp_f32_e32 v16, v16
	v_exp_f32_e32 v17, v17
	s_nop 0
	v_pk_add_f32 v[16:17], v[16:17], 1.0 op_sel_hi:[1,0]
	s_nop 0
	v_div_scale_f32 v18, s[10:11], v17, v17, v5
	v_rcp_f32_e32 v19, v18
	s_nop 0
	v_fma_f32 v20, -v18, v19, 1.0
	v_fmac_f32_e32 v19, v20, v19
	v_div_scale_f32 v20, vcc, v5, v17, v5
	v_mul_f32_e32 v21, v20, v19
	v_fma_f32 v22, -v18, v21, v20
	v_fmac_f32_e32 v21, v22, v19
	v_fma_f32 v18, -v18, v21, v20
	v_div_fmas_f32 v18, v18, v19, v21
	v_div_fixup_f32 v17, v18, v17, v5
	v_div_scale_f32 v5, s[10:11], v16, v16, v15
	v_rcp_f32_e32 v18, v5
	s_nop 0
	v_fma_f32 v19, -v5, v18, 1.0
	v_fmac_f32_e32 v18, v19, v18
	v_div_scale_f32 v19, vcc, v15, v16, v15
	v_mul_f32_e32 v20, v19, v18
	v_fma_f32 v21, -v5, v20, v19
	v_fmac_f32_e32 v20, v21, v18
	v_fma_f32 v5, -v5, v20, v19
	v_div_fmas_f32 v5, v5, v18, v20
	v_div_fixup_f32 v16, v5, v16, v15
	v_pk_mul_f32 v[12:13], v[16:17], v[12:13]
	s_nop 0
	v_cvt_pk_bf16_f32 v5, v12, v13
	v_lshl_add_u64 v[12:13], v[6:7], 0, s[0:1]
	v_add_co_u32_e32 v16, vcc, s5, v12
	s_mov_b32 s5, 0x21bb000
	s_nop 0
	v_addc_co_u32_e32 v17, vcc, 0, v13, vcc
	global_store_dwordx4 v[16:17], v[2:5], off offset:1536
	v_add_co_u32_e32 v16, vcc, s5, v10
	ds_read_b128 v[2:5], v14 offset:8704
	s_nop 0
	v_addc_co_u32_e32 v17, vcc, 0, v11, vcc
	global_load_dwordx4 v[16:19], v[16:17], off offset:1536
	s_mov_b32 s5, 0x373ab000
	s_waitcnt lgkmcnt(0)
	v_lshlrev_b32_e32 v20, 16, v2
	v_and_b32_e32 v21, 0xffff0000, v2
	v_lshl_add_u64 v[6:7], v[6:7], 0, s[14:15]
	s_waitcnt vmcnt(0)
	v_lshlrev_b32_e32 v15, 16, v16
	v_and_b32_e32 v2, 0xffff0000, v16
	v_mul_f32_e32 v16, 0xbfb8aa3b, v15
	v_exp_f32_e32 v22, v16
	v_mul_f32_e32 v16, 0xbfb8aa3b, v2
	v_exp_f32_e32 v23, v16
	s_nop 0
	v_pk_add_f32 v[22:23], v[22:23], 1.0 op_sel_hi:[1,0]
	s_nop 0
	v_div_scale_f32 v16, s[10:11], v23, v23, v2
	v_rcp_f32_e32 v24, v16
	s_nop 0
	v_fma_f32 v25, -v16, v24, 1.0
	v_fmac_f32_e32 v24, v25, v24
	v_div_scale_f32 v25, vcc, v2, v23, v2
	v_mul_f32_e32 v26, v25, v24
	v_fma_f32 v27, -v16, v26, v25
	v_fmac_f32_e32 v26, v27, v24
	v_fma_f32 v16, -v16, v26, v25
	v_div_fmas_f32 v16, v16, v24, v26
	v_div_fixup_f32 v23, v16, v23, v2
	v_div_scale_f32 v2, s[10:11], v22, v22, v15
	v_rcp_f32_e32 v16, v2
	s_nop 0
	v_fma_f32 v24, -v2, v16, 1.0
	v_fmac_f32_e32 v16, v24, v16
	v_div_scale_f32 v24, vcc, v15, v22, v15
	v_mul_f32_e32 v25, v24, v16
	v_fma_f32 v26, -v2, v25, v24
	v_fmac_f32_e32 v25, v26, v16
	v_fma_f32 v2, -v2, v25, v24
	v_div_fmas_f32 v2, v2, v16, v25
	v_div_fixup_f32 v22, v2, v22, v15
	v_pk_mul_f32 v[20:21], v[22:23], v[20:21]
	v_lshlrev_b32_e32 v15, 16, v17
	v_cvt_pk_bf16_f32 v2, v20, v21
	v_lshlrev_b32_e32 v20, 16, v3
	v_and_b32_e32 v21, 0xffff0000, v3
	v_and_b32_e32 v3, 0xffff0000, v17
	v_mul_f32_e32 v16, 0xbfb8aa3b, v15
	v_mul_f32_e32 v17, 0xbfb8aa3b, v3
	v_exp_f32_e32 v16, v16
	v_exp_f32_e32 v17, v17
	s_nop 0
	v_pk_add_f32 v[16:17], v[16:17], 1.0 op_sel_hi:[1,0]
	s_nop 0
	v_div_scale_f32 v22, s[10:11], v17, v17, v3
	v_rcp_f32_e32 v23, v22
	s_nop 0
	v_fma_f32 v24, -v22, v23, 1.0
	v_fmac_f32_e32 v23, v24, v23
	v_div_scale_f32 v24, vcc, v3, v17, v3
	v_mul_f32_e32 v25, v24, v23
	v_fma_f32 v26, -v22, v25, v24
	v_fmac_f32_e32 v25, v26, v23
	v_fma_f32 v22, -v22, v25, v24
	v_div_fmas_f32 v22, v22, v23, v25
	v_div_fixup_f32 v17, v22, v17, v3
	v_div_scale_f32 v3, s[10:11], v16, v16, v15
	v_rcp_f32_e32 v22, v3
	s_nop 0
	v_fma_f32 v23, -v3, v22, 1.0
	v_fmac_f32_e32 v22, v23, v22
	v_div_scale_f32 v23, vcc, v15, v16, v15
	v_mul_f32_e32 v24, v23, v22
	v_fma_f32 v25, -v3, v24, v23
	v_fmac_f32_e32 v24, v25, v22
	v_fma_f32 v3, -v3, v24, v23
	v_div_fmas_f32 v3, v3, v22, v24
	v_div_fixup_f32 v16, v3, v16, v15
	v_pk_mul_f32 v[16:17], v[16:17], v[20:21]
	v_lshlrev_b32_e32 v15, 16, v18
	v_cvt_pk_bf16_f32 v3, v16, v17
	v_lshlrev_b32_e32 v16, 16, v4
	v_and_b32_e32 v17, 0xffff0000, v4
	v_and_b32_e32 v4, 0xffff0000, v18
	v_mul_f32_e32 v18, 0xbfb8aa3b, v15
	v_exp_f32_e32 v20, v18
	v_mul_f32_e32 v18, 0xbfb8aa3b, v4
	v_exp_f32_e32 v21, v18
	s_nop 0
	v_pk_add_f32 v[20:21], v[20:21], 1.0 op_sel_hi:[1,0]
	s_nop 0
	v_div_scale_f32 v18, s[10:11], v21, v21, v4
	v_rcp_f32_e32 v22, v18
	s_nop 0
	v_fma_f32 v23, -v18, v22, 1.0
	v_fmac_f32_e32 v22, v23, v22
	v_div_scale_f32 v23, vcc, v4, v21, v4
	v_mul_f32_e32 v24, v23, v22
	v_fma_f32 v25, -v18, v24, v23
	v_fmac_f32_e32 v24, v25, v22
	v_fma_f32 v18, -v18, v24, v23
	v_div_fmas_f32 v18, v18, v22, v24
	v_div_fixup_f32 v21, v18, v21, v4
	v_div_scale_f32 v4, s[10:11], v20, v20, v15
	v_rcp_f32_e32 v18, v4
	s_nop 0
	v_fma_f32 v22, -v4, v18, 1.0
	v_fmac_f32_e32 v18, v22, v18
	v_div_scale_f32 v22, vcc, v15, v20, v15
	v_mul_f32_e32 v23, v22, v18
	v_fma_f32 v24, -v4, v23, v22
	v_fmac_f32_e32 v23, v24, v18
	v_fma_f32 v4, -v4, v23, v22
	v_div_fmas_f32 v4, v4, v18, v23
	v_div_fixup_f32 v20, v4, v20, v15
	v_pk_mul_f32 v[16:17], v[20:21], v[16:17]
	v_lshlrev_b32_e32 v15, 16, v19
	v_cvt_pk_bf16_f32 v4, v16, v17
	v_lshlrev_b32_e32 v16, 16, v5
	v_and_b32_e32 v17, 0xffff0000, v5
	v_and_b32_e32 v5, 0xffff0000, v19
	v_mul_f32_e32 v18, 0xbfb8aa3b, v15
	v_mul_f32_e32 v19, 0xbfb8aa3b, v5
	v_exp_f32_e32 v18, v18
	v_exp_f32_e32 v19, v19
	s_nop 0
	v_pk_add_f32 v[18:19], v[18:19], 1.0 op_sel_hi:[1,0]
	s_nop 0
	v_div_scale_f32 v20, s[10:11], v19, v19, v5
	v_rcp_f32_e32 v21, v20
	s_nop 0
	v_fma_f32 v22, -v20, v21, 1.0
	v_fmac_f32_e32 v21, v22, v21
	v_div_scale_f32 v22, vcc, v5, v19, v5
	v_mul_f32_e32 v23, v22, v21
	v_fma_f32 v24, -v20, v23, v22
	v_fmac_f32_e32 v23, v24, v21
	v_fma_f32 v20, -v20, v23, v22
	v_div_fmas_f32 v20, v20, v21, v23
	v_div_fixup_f32 v19, v20, v19, v5
	v_div_scale_f32 v5, s[10:11], v18, v18, v15
	v_rcp_f32_e32 v20, v5
	s_nop 0
	v_fma_f32 v21, -v5, v20, 1.0
	v_fmac_f32_e32 v20, v21, v20
	v_div_scale_f32 v21, vcc, v15, v18, v15
	v_mul_f32_e32 v22, v21, v20
	v_fma_f32 v23, -v5, v22, v21
	v_fmac_f32_e32 v22, v23, v20
	v_fma_f32 v5, -v5, v22, v21
	v_div_fmas_f32 v5, v5, v20, v22
	v_div_fixup_f32 v18, v5, v18, v15
	v_pk_mul_f32 v[16:17], v[18:19], v[16:17]
	s_nop 0
	v_cvt_pk_bf16_f32 v5, v16, v17
	v_add_co_u32_e32 v16, vcc, s5, v12
	s_mov_b32 s5, 0x21db000
	s_nop 0
	v_addc_co_u32_e32 v17, vcc, 0, v13, vcc
	global_store_dwordx4 v[16:17], v[2:5], off offset:1536
	v_add_co_u32_e32 v16, vcc, s5, v10
	ds_read_b128 v[2:5], v14 offset:17408
	s_nop 0
	v_addc_co_u32_e32 v17, vcc, 0, v11, vcc
	global_load_dwordx4 v[16:19], v[16:17], off offset:1536
	s_mov_b32 s5, 0x373bb000
	s_waitcnt lgkmcnt(0)
	v_lshlrev_b32_e32 v20, 16, v2
	v_and_b32_e32 v21, 0xffff0000, v2
	s_waitcnt vmcnt(0)
	v_lshlrev_b32_e32 v15, 16, v16
	v_and_b32_e32 v2, 0xffff0000, v16
	v_mul_f32_e32 v16, 0xbfb8aa3b, v15
	v_exp_f32_e32 v22, v16
	v_mul_f32_e32 v16, 0xbfb8aa3b, v2
	v_exp_f32_e32 v23, v16
	s_nop 0
	v_pk_add_f32 v[22:23], v[22:23], 1.0 op_sel_hi:[1,0]
	s_nop 0
	v_div_scale_f32 v16, s[10:11], v23, v23, v2
	v_rcp_f32_e32 v24, v16
	s_nop 0
	v_fma_f32 v25, -v16, v24, 1.0
	v_fmac_f32_e32 v24, v25, v24
	v_div_scale_f32 v25, vcc, v2, v23, v2
	v_mul_f32_e32 v26, v25, v24
	v_fma_f32 v27, -v16, v26, v25
	v_fmac_f32_e32 v26, v27, v24
	v_fma_f32 v16, -v16, v26, v25
	v_div_fmas_f32 v16, v16, v24, v26
	v_div_fixup_f32 v23, v16, v23, v2
	v_div_scale_f32 v2, s[10:11], v22, v22, v15
	v_rcp_f32_e32 v16, v2
	s_nop 0
	v_fma_f32 v24, -v2, v16, 1.0
	v_fmac_f32_e32 v16, v24, v16
	v_div_scale_f32 v24, vcc, v15, v22, v15
	v_mul_f32_e32 v25, v24, v16
	v_fma_f32 v26, -v2, v25, v24
	v_fmac_f32_e32 v25, v26, v16
	v_fma_f32 v2, -v2, v25, v24
	v_div_fmas_f32 v2, v2, v16, v25
	v_div_fixup_f32 v22, v2, v22, v15
	v_pk_mul_f32 v[20:21], v[22:23], v[20:21]
	v_lshlrev_b32_e32 v15, 16, v17
	v_cvt_pk_bf16_f32 v2, v20, v21
	v_lshlrev_b32_e32 v20, 16, v3
	v_and_b32_e32 v21, 0xffff0000, v3
	v_and_b32_e32 v3, 0xffff0000, v17
	v_mul_f32_e32 v16, 0xbfb8aa3b, v15
	v_mul_f32_e32 v17, 0xbfb8aa3b, v3
	v_exp_f32_e32 v16, v16
	v_exp_f32_e32 v17, v17
	s_nop 0
	v_pk_add_f32 v[16:17], v[16:17], 1.0 op_sel_hi:[1,0]
	s_nop 0
	v_div_scale_f32 v22, s[10:11], v17, v17, v3
	v_rcp_f32_e32 v23, v22
	s_nop 0
	v_fma_f32 v24, -v22, v23, 1.0
	v_fmac_f32_e32 v23, v24, v23
	v_div_scale_f32 v24, vcc, v3, v17, v3
	v_mul_f32_e32 v25, v24, v23
	v_fma_f32 v26, -v22, v25, v24
	v_fmac_f32_e32 v25, v26, v23
	v_fma_f32 v22, -v22, v25, v24
	v_div_fmas_f32 v22, v22, v23, v25
	v_div_fixup_f32 v17, v22, v17, v3
	v_div_scale_f32 v3, s[10:11], v16, v16, v15
	v_rcp_f32_e32 v22, v3
	s_nop 0
	v_fma_f32 v23, -v3, v22, 1.0
	v_fmac_f32_e32 v22, v23, v22
	v_div_scale_f32 v23, vcc, v15, v16, v15
	v_mul_f32_e32 v24, v23, v22
	v_fma_f32 v25, -v3, v24, v23
	v_fmac_f32_e32 v24, v25, v22
	v_fma_f32 v3, -v3, v24, v23
	v_div_fmas_f32 v3, v3, v22, v24
	v_div_fixup_f32 v16, v3, v16, v15
	v_pk_mul_f32 v[16:17], v[16:17], v[20:21]
	v_lshlrev_b32_e32 v15, 16, v18
	v_cvt_pk_bf16_f32 v3, v16, v17
	v_lshlrev_b32_e32 v16, 16, v4
	v_and_b32_e32 v17, 0xffff0000, v4
	v_and_b32_e32 v4, 0xffff0000, v18
	v_mul_f32_e32 v18, 0xbfb8aa3b, v15
	v_exp_f32_e32 v20, v18
	v_mul_f32_e32 v18, 0xbfb8aa3b, v4
	v_exp_f32_e32 v21, v18
	s_nop 0
	v_pk_add_f32 v[20:21], v[20:21], 1.0 op_sel_hi:[1,0]
	s_nop 0
	v_div_scale_f32 v18, s[10:11], v21, v21, v4
	v_rcp_f32_e32 v22, v18
	s_nop 0
	v_fma_f32 v23, -v18, v22, 1.0
	v_fmac_f32_e32 v22, v23, v22
	v_div_scale_f32 v23, vcc, v4, v21, v4
	v_mul_f32_e32 v24, v23, v22
	v_fma_f32 v25, -v18, v24, v23
	v_fmac_f32_e32 v24, v25, v22
	v_fma_f32 v18, -v18, v24, v23
	v_div_fmas_f32 v18, v18, v22, v24
	v_div_fixup_f32 v21, v18, v21, v4
	v_div_scale_f32 v4, s[10:11], v20, v20, v15
	v_rcp_f32_e32 v18, v4
	s_nop 0
	v_fma_f32 v22, -v4, v18, 1.0
	v_fmac_f32_e32 v18, v22, v18
	v_div_scale_f32 v22, vcc, v15, v20, v15
	v_mul_f32_e32 v23, v22, v18
	v_fma_f32 v24, -v4, v23, v22
	v_fmac_f32_e32 v23, v24, v18
	v_fma_f32 v4, -v4, v23, v22
	v_div_fmas_f32 v4, v4, v18, v23
	v_div_fixup_f32 v20, v4, v20, v15
	v_pk_mul_f32 v[16:17], v[20:21], v[16:17]
	v_lshlrev_b32_e32 v15, 16, v19
	v_cvt_pk_bf16_f32 v4, v16, v17
	v_lshlrev_b32_e32 v16, 16, v5
	v_and_b32_e32 v17, 0xffff0000, v5
	v_and_b32_e32 v5, 0xffff0000, v19
	v_mul_f32_e32 v18, 0xbfb8aa3b, v15
	v_mul_f32_e32 v19, 0xbfb8aa3b, v5
	v_exp_f32_e32 v18, v18
	v_exp_f32_e32 v19, v19
	s_nop 0
	v_pk_add_f32 v[18:19], v[18:19], 1.0 op_sel_hi:[1,0]
	s_nop 0
	v_div_scale_f32 v20, s[10:11], v19, v19, v5
	v_rcp_f32_e32 v21, v20
	s_nop 0
	v_fma_f32 v22, -v20, v21, 1.0
	v_fmac_f32_e32 v21, v22, v21
	v_div_scale_f32 v22, vcc, v5, v19, v5
	v_mul_f32_e32 v23, v22, v21
	v_fma_f32 v24, -v20, v23, v22
	v_fmac_f32_e32 v23, v24, v21
	v_fma_f32 v20, -v20, v23, v22
	v_div_fmas_f32 v20, v20, v21, v23
	v_div_fixup_f32 v19, v20, v19, v5
	v_div_scale_f32 v5, s[10:11], v18, v18, v15
	v_rcp_f32_e32 v20, v5
	s_nop 0
	v_fma_f32 v21, -v5, v20, 1.0
	v_fmac_f32_e32 v20, v21, v20
	v_div_scale_f32 v21, vcc, v15, v18, v15
	v_mul_f32_e32 v22, v21, v20
	v_fma_f32 v23, -v5, v22, v21
	v_fmac_f32_e32 v22, v23, v20
	v_fma_f32 v5, -v5, v22, v21
	v_div_fmas_f32 v5, v5, v20, v22
	v_div_fixup_f32 v18, v5, v18, v15
	v_pk_mul_f32 v[16:17], v[18:19], v[16:17]
	s_nop 0
	v_cvt_pk_bf16_f32 v5, v16, v17
	v_add_co_u32_e32 v16, vcc, s5, v12
	s_mov_b32 s5, 0x21fb000
	s_nop 0
	v_addc_co_u32_e32 v17, vcc, 0, v13, vcc
	v_add_co_u32_e32 v10, vcc, s5, v10
	global_store_dwordx4 v[16:17], v[2:5], off offset:1536
	s_nop 0
	v_addc_co_u32_e32 v11, vcc, 0, v11, vcc
	ds_read_b128 v[2:5], v14 offset:26112
	global_load_dwordx4 v[14:17], v[10:11], off offset:1536
	s_waitcnt lgkmcnt(0)
	v_lshlrev_b32_e32 v10, 16, v2
	v_and_b32_e32 v11, 0xffff0000, v2
	s_waitcnt vmcnt(0)
	v_lshlrev_b32_e32 v20, 16, v14
	v_and_b32_e32 v2, 0xffff0000, v14
	v_mul_f32_e32 v14, 0xbfb8aa3b, v20
	v_exp_f32_e32 v18, v14
	v_mul_f32_e32 v14, 0xbfb8aa3b, v2
	v_exp_f32_e32 v19, v14
	s_nop 0
	v_pk_add_f32 v[18:19], v[18:19], 1.0 op_sel_hi:[1,0]
	s_nop 0
	v_div_scale_f32 v14, s[10:11], v19, v19, v2
	v_rcp_f32_e32 v21, v14
	s_nop 0
	v_fma_f32 v22, -v14, v21, 1.0
	v_fmac_f32_e32 v21, v22, v21
	v_div_scale_f32 v22, vcc, v2, v19, v2
	v_mul_f32_e32 v23, v22, v21
	v_fma_f32 v24, -v14, v23, v22
	v_fmac_f32_e32 v23, v24, v21
	v_fma_f32 v14, -v14, v23, v22
	v_div_fmas_f32 v14, v14, v21, v23
	v_div_fixup_f32 v19, v14, v19, v2
	v_div_scale_f32 v2, s[10:11], v18, v18, v20
	v_rcp_f32_e32 v14, v2
	s_nop 0
	v_fma_f32 v21, -v2, v14, 1.0
	v_fmac_f32_e32 v14, v21, v14
	v_div_scale_f32 v21, vcc, v20, v18, v20
	v_mul_f32_e32 v22, v21, v14
	v_fma_f32 v23, -v2, v22, v21
	v_fmac_f32_e32 v22, v23, v14
	v_fma_f32 v2, -v2, v22, v21
	v_div_fmas_f32 v2, v2, v14, v22
	v_div_fixup_f32 v18, v2, v18, v20
	v_pk_mul_f32 v[10:11], v[18:19], v[10:11]
	v_lshlrev_b32_e32 v18, 16, v15
	v_cvt_pk_bf16_f32 v2, v10, v11
	v_lshlrev_b32_e32 v10, 16, v3
	v_and_b32_e32 v11, 0xffff0000, v3
	v_and_b32_e32 v3, 0xffff0000, v15
	v_mul_f32_e32 v14, 0xbfb8aa3b, v18
	v_mul_f32_e32 v15, 0xbfb8aa3b, v3
	v_exp_f32_e32 v14, v14
	v_exp_f32_e32 v15, v15
	s_nop 0
	v_pk_add_f32 v[14:15], v[14:15], 1.0 op_sel_hi:[1,0]
	s_nop 0
	v_div_scale_f32 v19, s[10:11], v15, v15, v3
	v_rcp_f32_e32 v20, v19
	s_nop 0
	v_fma_f32 v21, -v19, v20, 1.0
	v_fmac_f32_e32 v20, v21, v20
	v_div_scale_f32 v21, vcc, v3, v15, v3
	v_mul_f32_e32 v22, v21, v20
	v_fma_f32 v23, -v19, v22, v21
	v_fmac_f32_e32 v22, v23, v20
	v_fma_f32 v19, -v19, v22, v21
	v_div_fmas_f32 v19, v19, v20, v22
	v_div_fixup_f32 v15, v19, v15, v3
	v_div_scale_f32 v3, s[10:11], v14, v14, v18
	v_rcp_f32_e32 v19, v3
	s_nop 0
	v_fma_f32 v20, -v3, v19, 1.0
	v_fmac_f32_e32 v19, v20, v19
	v_div_scale_f32 v20, vcc, v18, v14, v18
	v_mul_f32_e32 v21, v20, v19
	v_fma_f32 v22, -v3, v21, v20
	v_fmac_f32_e32 v21, v22, v19
	v_fma_f32 v3, -v3, v21, v20
	v_div_fmas_f32 v3, v3, v19, v21
	v_div_fixup_f32 v14, v3, v14, v18
	v_pk_mul_f32 v[10:11], v[14:15], v[10:11]
	v_lshlrev_b32_e32 v18, 16, v16
	v_cvt_pk_bf16_f32 v3, v10, v11
	v_lshlrev_b32_e32 v10, 16, v4
	v_and_b32_e32 v11, 0xffff0000, v4
	v_and_b32_e32 v4, 0xffff0000, v16
	v_mul_f32_e32 v14, 0xbfb8aa3b, v18
	v_mul_f32_e32 v15, 0xbfb8aa3b, v4
	v_exp_f32_e32 v14, v14
	v_exp_f32_e32 v15, v15
	s_nop 0
	v_pk_add_f32 v[14:15], v[14:15], 1.0 op_sel_hi:[1,0]
	s_nop 0
	v_div_scale_f32 v16, s[10:11], v15, v15, v4
	v_rcp_f32_e32 v19, v16
	s_nop 0
	v_fma_f32 v20, -v16, v19, 1.0
	v_fmac_f32_e32 v19, v20, v19
	v_div_scale_f32 v20, vcc, v4, v15, v4
	v_mul_f32_e32 v21, v20, v19
	v_fma_f32 v22, -v16, v21, v20
	v_fmac_f32_e32 v21, v22, v19
	v_fma_f32 v16, -v16, v21, v20
	v_div_fmas_f32 v16, v16, v19, v21
	v_div_fixup_f32 v15, v16, v15, v4
	v_div_scale_f32 v4, s[10:11], v14, v14, v18
	v_rcp_f32_e32 v16, v4
	s_nop 0
	v_fma_f32 v19, -v4, v16, 1.0
	v_fmac_f32_e32 v16, v19, v16
	v_div_scale_f32 v19, vcc, v18, v14, v18
	v_mul_f32_e32 v20, v19, v16
	v_fma_f32 v21, -v4, v20, v19
	v_fmac_f32_e32 v20, v21, v16
	v_fma_f32 v4, -v4, v20, v19
	v_div_fmas_f32 v4, v4, v16, v20
	v_div_fixup_f32 v14, v4, v14, v18
	v_pk_mul_f32 v[10:11], v[14:15], v[10:11]
	v_lshlrev_b32_e32 v16, 16, v17
	v_cvt_pk_bf16_f32 v4, v10, v11
	v_lshlrev_b32_e32 v10, 16, v5
	v_and_b32_e32 v11, 0xffff0000, v5
	v_and_b32_e32 v5, 0xffff0000, v17
	v_mul_f32_e32 v14, 0xbfb8aa3b, v16
	v_mul_f32_e32 v15, 0xbfb8aa3b, v5
	v_exp_f32_e32 v14, v14
	v_exp_f32_e32 v15, v15
	s_nop 0
	v_pk_add_f32 v[14:15], v[14:15], 1.0 op_sel_hi:[1,0]
	s_nop 0
	v_div_scale_f32 v17, s[10:11], v15, v15, v5
	v_rcp_f32_e32 v18, v17
	s_nop 0
	v_fma_f32 v19, -v17, v18, 1.0
	v_fmac_f32_e32 v18, v19, v18
	v_div_scale_f32 v19, vcc, v5, v15, v5
	v_mul_f32_e32 v20, v19, v18
	v_fma_f32 v21, -v17, v20, v19
	v_fmac_f32_e32 v20, v21, v18
	v_fma_f32 v17, -v17, v20, v19
	v_div_fmas_f32 v17, v17, v18, v20
	v_div_fixup_f32 v15, v17, v15, v5
	v_div_scale_f32 v5, s[10:11], v14, v14, v16
	v_rcp_f32_e32 v17, v5
	s_nop 0
	v_fma_f32 v18, -v5, v17, 1.0
	v_fmac_f32_e32 v17, v18, v17
	v_div_scale_f32 v18, vcc, v16, v14, v16
	v_mul_f32_e32 v19, v18, v17
	v_fma_f32 v20, -v5, v19, v18
	v_fmac_f32_e32 v19, v20, v17
	v_fma_f32 v5, -v5, v19, v18
	v_div_fmas_f32 v5, v5, v17, v19
	v_div_fixup_f32 v14, v5, v14, v16
	v_pk_mul_f32 v[10:11], v[14:15], v[10:11]
	s_nop 0
	v_cvt_pk_bf16_f32 v5, v10, v11
	v_add_co_u32_e32 v10, vcc, 0x373cb000, v12
	s_nop 1
	v_addc_co_u32_e32 v11, vcc, 0, v13, vcc
	global_store_dwordx4 v[10:11], v[2:5], off offset:1536
	s_cbranch_scc0 .LBB0_41
	v_readlane_b32 s4, v254, 3
	s_add_i32 s6, s6, s4
	s_cmpk_gt_i32 s6, 0x4ff
	s_barrier
	s_cbranch_scc1 .Lp4_attn_fin
	v_readlane_b32 vcc_lo, v255, 62
	v_readlane_b32 vcc_hi, v255, 60
	s_nop 3
	s_cmp_eq_u32 vcc_lo, 0
	s_cbranch_scc0 .LBB0_21
	s_lshr_b32 vcc_lo, s6, 8
	s_cmp_eq_u32 vcc_lo, vcc_hi
	s_cbranch_scc0 .LBB0_21
	s_nop 0
	v_writelane_b32 v255, s6, 61
	s_branch .LBB0_43
.Lp4_attn_fin:
	v_readlane_b32 s0, v255, 62
	s_nop 3
	s_cmp_eq_u32 s0, 2
	s_cbranch_scc0 .Lp4_ret_last
	s_mov_b32 s0, 0
	s_nop 0
	v_writelane_b32 v255, s0, 62
	s_branch .LBB0_94
.Lp4_ret_last:
	v_writelane_b32 v255, s6, 61

.Lp4_ret_done:
	s_mov_b32 s0, 2
	s_nop 0
	v_writelane_b32 v255, s0, 62
	s_branch .Lp4_attn_entry
